# outnt: the final f32 module output (written once, never re-read) stored with nt streaming hint; on top of xbpre
# baseline (speedup 1.0000x reference)
.LBB0_908:
	s_andn2_b64 vcc, exec, s[10:11]
	v_lshl_add_u64 v[132:133], v[132:133], 2, s[16:17]
	s_cbranch_vccnz .LBB0_910
	global_store_dwordx4 v[132:133], v[18:21], off nt
	global_store_dwordx4 v[132:133], v[22:25], off offset:16 nt

.LBB0_912:
	s_andn2_b64 vcc, exec, s[10:11]
	v_lshl_add_u64 v[124:125], v[124:125], 2, s[16:17]
	s_cbranch_vccnz .LBB0_914
	global_store_dwordx4 v[124:125], v[18:21], off nt
	global_store_dwordx4 v[124:125], v[22:25], off offset:16 nt

.LBB0_916:
	s_andn2_b64 vcc, exec, s[10:11]
	v_lshl_add_u64 v[116:117], v[116:117], 2, s[16:17]
	s_cbranch_vccnz .LBB0_918
	global_store_dwordx4 v[116:117], v[18:21], off nt
	global_store_dwordx4 v[116:117], v[22:25], off offset:16 nt

.LBB0_920:
	s_andn2_b64 vcc, exec, s[10:11]
	v_lshl_add_u64 v[108:109], v[108:109], 2, s[16:17]
	s_cbranch_vccnz .LBB0_922
	global_store_dwordx4 v[108:109], v[18:21], off nt
	global_store_dwordx4 v[108:109], v[22:25], off offset:16 nt

.LBB0_924:
	s_andn2_b64 vcc, exec, s[10:11]
	v_lshl_add_u64 v[100:101], v[100:101], 2, s[16:17]
	s_cbranch_vccnz .LBB0_926
	global_store_dwordx4 v[100:101], v[18:21], off nt
	global_store_dwordx4 v[100:101], v[22:25], off offset:16 nt

.LBB0_928:
	s_andn2_b64 vcc, exec, s[10:11]
	v_lshl_add_u64 v[92:93], v[92:93], 2, s[16:17]
	s_cbranch_vccnz .LBB0_930
	global_store_dwordx4 v[92:93], v[18:21], off nt
	global_store_dwordx4 v[92:93], v[22:25], off offset:16 nt

.LBB0_932:
	s_andn2_b64 vcc, exec, s[10:11]
	v_lshl_add_u64 v[84:85], v[84:85], 2, s[16:17]
	s_cbranch_vccnz .LBB0_934
	global_store_dwordx4 v[84:85], v[18:21], off nt
	global_store_dwordx4 v[84:85], v[22:25], off offset:16 nt

.LBB0_936:
	s_andn2_b64 vcc, exec, s[10:11]
	v_lshl_add_u64 v[88:89], v[10:11], 2, s[16:17]
	s_cbranch_vccnz .LBB0_938
	global_store_dwordx4 v[88:89], v[6:9], off nt
	global_store_dwordx4 v[88:89], v[2:5], off offset:16 nt

.LBB0_943:
	s_andn2_b64 vcc, exec, s[10:11]
	s_cbranch_vccnz .LBB0_945
	global_store_dwordx4 v[132:133], v[18:21], off offset:512 nt
	global_store_dwordx4 v[132:133], v[22:25], off offset:528 nt

.LBB0_947:
	s_andn2_b64 vcc, exec, s[10:11]
	s_cbranch_vccnz .LBB0_949
	global_store_dwordx4 v[124:125], v[18:21], off offset:512 nt
	global_store_dwordx4 v[124:125], v[22:25], off offset:528 nt

.LBB0_951:
	s_andn2_b64 vcc, exec, s[10:11]
	s_cbranch_vccnz .LBB0_953
	global_store_dwordx4 v[116:117], v[18:21], off offset:512 nt
	global_store_dwordx4 v[116:117], v[22:25], off offset:528 nt

.LBB0_955:
	s_andn2_b64 vcc, exec, s[10:11]
	s_cbranch_vccnz .LBB0_957
	global_store_dwordx4 v[108:109], v[18:21], off offset:512 nt
	global_store_dwordx4 v[108:109], v[22:25], off offset:528 nt

.LBB0_959:
	s_andn2_b64 vcc, exec, s[10:11]
	s_cbranch_vccnz .LBB0_961
	global_store_dwordx4 v[100:101], v[18:21], off offset:512 nt
	global_store_dwordx4 v[100:101], v[22:25], off offset:528 nt

.LBB0_963:
	s_andn2_b64 vcc, exec, s[10:11]
	s_cbranch_vccnz .LBB0_965
	global_store_dwordx4 v[92:93], v[18:21], off offset:512 nt
	global_store_dwordx4 v[92:93], v[22:25], off offset:528 nt

.LBB0_967:
	s_andn2_b64 vcc, exec, s[10:11]
	s_cbranch_vccnz .LBB0_969
	global_store_dwordx4 v[84:85], v[18:21], off offset:512 nt
	global_store_dwordx4 v[84:85], v[22:25], off offset:528 nt

.LBB0_971:
	s_andn2_b64 vcc, exec, s[8:9]
	s_cbranch_vccnz .LBB0_973
	global_store_dwordx4 v[88:89], v[6:9], off offset:512 nt
	global_store_dwordx4 v[88:89], v[2:5], off offset:528 nt
